# residual GEMM phases: CUs that own two units run their split-K tail unit first so the H read-modify-write epilogues of the 256 main tiles do not all start together
# baseline (speedup 1.0000x reference)
;     DI bool next(int i, Unit& u) const {
;         const long L = (long)i * G + c; if (L >= nwg + nwg2 + nsplit) return false;
;         u.k0 = 0; u.nt = ntK; u.kind = 0;
;         if (L < nwg) { tile((int)L, nwg, nM, nN, u); return true; }
;         if (L < nwg + nwg2) { tile((int)L - nwg, nwg2, nM2, nN2, u); u.kind = 1; return true; }
;         const int L2 = (int)L - nwg - nwg2; const int sl = L2 % nsl, tl = L2 / nsl; u.pm = nM + (tl & 3); u.pn = tl >> 2; u.k0 = sl * 256; u.nt = 4; return true;
;     }
; template <class Epi>
; DI void gemm_phase(LAS unsigned char* lds, const Gemm g, const StaticOrder S, const Epi E) {
;     ...
;     Unit cur, nxt; int ui = 0;
;     if (!S.next(0, cur)) return;
.LBB0_405:
	s_cmp_gt_u32 s49, 6
	v_readlane_b32 s0, v254, 49
	s_cselect_b64 s[2:3], -1, 0
	v_readlane_b32 s1, v254, 50
	s_and_b64 s[2:3], s[0:1], s[2:3]
	s_and_b64 s[2:3], s[2:3], exec
	s_cselect_b32 s2, 0, 16
	s_lshr_b32 s76, s7, 8
	s_mul_i32 s2, s76, s2
	s_lshr_b32 s0, s7, 6
	s_or_b32 s48, s2, 0x100
	s_waitcnt vmcnt(0)
	v_mov_b32_e32 v12, v200
	s_cmp_lt_i32 s92, s48
	s_cselect_b64 s[30:31], -1, 0
	s_cmp_ge_i32 s92, s48
	v_readfirstlane_b32 s37, v12
	s_cbranch_scc1 .LBB0_410
	s_cmp_eq_u32 s93, 0x100
	s_cselect_b32 s20, s48, 0
	s_add_i32 s21, s92, 0x100
	s_cmp_lt_i32 s21, s20
	s_mov_b64 s[40:41], -1
	s_cbranch_scc0 .LBB0_408
	v_cvt_f32_ubyte1_e32 v1, s7
	v_rcp_iflag_f32_e32 v2, v1
	v_cvt_f32_ubyte0_e32 v0, s92
	s_mov_b64 s[40:41], 0
	v_mul_f32_e32 v2, v0, v2
	v_trunc_f32_e32 v2, v2
	v_fma_f32 v0, -v2, v1, v0
	v_cvt_u32_f32_e32 v2, v2
	v_cmp_ge_f32_e64 s[2:3], |v0|, v1
	s_cmp_lg_u64 s[2:3], 0
	v_readfirstlane_b32 s20, v2
	s_addc_u32 s2, s20, 0
	s_mul_i32 s3, s2, s76
	s_sub_i32 s3, s92, s3
	s_and_b32 s20, s3, 0xff
	s_and_b32 s3, s2, 3
	s_or_b32 s3, s3, 64
	s_bfe_u32 s78, s2, 0x60002
	s_lshl_b32 s50, s20, 8

;     DI bool next(int i, Unit& u) const {
;         const long L = (long)i * G + c; if (L >= nwg + nwg2 + nsplit) return false;
;         u.k0 = 0; u.nt = ntK; u.kind = 0;
;         if (L < nwg) { tile((int)L, nwg, nM, nN, u); return true; }
;         if (L < nwg + nwg2) { tile((int)L - nwg, nwg2, nM2, nN2, u); u.kind = 1; return true; }
;         const int L2 = (int)L - nwg - nwg2; const int sl = L2 % nsl, tl = L2 / nsl; u.pm = nM + (tl & 3); u.pn = tl >> 2; u.k0 = sl * 256; u.nt = 4; return true;
;     }
; template <class Epi>
; DI void gemm_phase(LAS unsigned char* lds, const Gemm g, const StaticOrder S, const Epi E) {
;     ...
;         const bool has_next = S.next(ui + 1, nxt);
.LBB0_416:
	s_add_i32 s71, s71, 1
	v_readlane_b32 s0, v254, 54
	s_mul_i32 s20, s71, s0
	s_mul_hi_u32 s21, s71, s93
	s_add_i32 s21, s21, s20
	s_mul_i32 s20, s71, s93
	s_add_u32 s40, s20, s92
	v_readlane_b32 s0, v254, 53
	s_addc_u32 s41, s21, s0
	s_cmp_eq_u32 s71, 1
	s_cbranch_scc0 .Lgm_swap_no
	s_cmp_eq_u32 s93, 0x100
	s_cselect_b32 s20, s48, 0
	s_add_i32 s21, s92, 0x100
	s_cmp_lt_i32 s21, s20
	s_cbranch_scc0 .Lgm_swap_no
	s_mov_b32 s40, s92
	s_mov_b32 s41, 0
.Lgm_swap_no:
	v_mov_b64_e32 v[0:1], s[48:49]
	v_cmp_ge_i64_e32 vcc, s[40:41], v[0:1]
	v_cmp_lt_i64_e64 s[42:43], s[40:41], v[0:1]
	s_cbranch_vccnz .LBB0_425
	v_cmp_gt_i64_e32 vcc, s[40:41], v[154:155]
	s_mov_b64 s[66:67], -1
	s_cbranch_vccz .LBB0_419
	s_add_i32 s20, s40, 0xffffff00
	s_mul_hi_u32 s21, s20, s9
	s_mul_i32 s37, s21, s76
	s_sub_i32 s37, s20, s37
	s_add_i32 s41, s21, 1
	s_sub_i32 s64, s37, s76
	s_cmp_ge_u32 s37, s76
	s_cselect_b32 s21, s41, s21
	s_cselect_b32 s37, s64, s37
	s_add_i32 s41, s21, 1
	s_cmp_ge_u32 s37, s76
	s_cselect_b32 s21, s41, s21
	s_mul_i32 s37, s21, s76
	s_sub_i32 s20, s20, s37
	s_and_b32 s37, s21, 3
	s_or_b32 s79, s37, 64
	s_ashr_i32 s83, s21, 2
	s_lshl_b32 s64, s20, 8
	s_mov_b64 s[66:67], 0
